# RG-LRU scan phase: sample-sequence units spread over all 32 workgroups (waves 0-3, wl=4*rank+wave) instead of ranks<16 with 8 waves
# baseline (speedup 1.0000x reference)
; #define LAS __attribute__((address_space(3)))
; DI void rg_unit_setup(ArgsP A, int j, int cb, int nt, int lane, LAS float* cw, bf16x8 (&Ba)[4], bf16x8 (&Bx)[4], float& ba, float& bx, float& spn, float (&cwo)[5]) {
;     const int r = lane & 31, hh = lane >> 5, cho = cb * 64 + 32 * nt + r;
;     const bf16* WG = (const bf16*)(A->ws + WS_WG) + (size_t)(j * 2) * 64 * DM;
; #pragma unroll
;     for (int kk = 0; kk < 4; ++kk) { Ba[kk] = *(const bf16x8*)(WG + (size_t)(32 * nt + r) * DM + cb * 64 + 16 * kk + 8 * hh); Bx[kk] = *(const bf16x8*)(WG + (size_t)64 * DM + (size_t)(32 * nt + r) * DM + cb * 64 + 16 * kk + 8 * hh); }
;     ba = A->in[I_RGBA][j * DM + cho]; bx = A->in[I_RGBX][j * DM + cho];
;     const float lam = A->in[I_RGLAM][j * DM + cho];
;     spn = -8.0f * log1pf(expf(-lam));
; #pragma unroll
;     for (int q = 0; q < 4; ++q) { cwo[q] = A->in[I_RGCW][(size_t)(j * 4 + q) * DM + cho]; cw[q * 64 + lane] = A->in[I_RGCW][(size_t)(j * 4 + q) * DM + cb * 64 + lane]; }
;     cwo[4] = A->in[I_RGCB][j * DM + cho]; cw[256 + lane] = A->in[I_RGCB][j * DM + cb * 64 + lane];
; DI void rg_sample_unit(ArgsP A, LAS unsigned char* lds, int j, int wu, int wave, int lane) {
;     const int nt = wu & 1, cb = (wu >> 1) & 15, sg = wu >> 5;
;     const int r = lane & 31, hh = lane >> 5, cho = cb * 64 + 32 * nt + r, chA = cb * 64;
;     LAS unsigned char* xs = lds + wave * 6400;
;     LAS float* cw = (LAS float*)(lds + 51200 + wave * 1280);
;     const bf16* XBR = (const bf16*)(A->ws + WS_A2); const bf16* GATE = (const bf16*)(A->ws + WS_A1); bf16* HG = (bf16*)(A->ws + WS_A3);
;     bf16x8 Ba[4], Bx[4]; float ba, bx, spn, cwo[5];
;     rg_unit_setup(A, j, cb, nt, lane, cw, Ba, Bx, ba, bx, spn, cwo);
; #pragma unroll
;     for (int i = 0; i < 6; ++i) { const int id = lane + 64 * i; if (id < 352) { const int row = id >> 3, c16 = id & 7, sq = row / 11, rr = row - 11 * sq, bb = 4 * sg + sq; u32x4 v;
;             if (rr < 3) { const float* cp = A->in[I_RGCONV] + ((size_t)(j * 128 + bb) * 3 + rr) * DM + chA + c16 * 8; const f32x4 f0 = *(const f32x4*)cp, f1 = *(const f32x4*)(cp + 4);
;                 v.x = pk2(f0[0], f0[1]); v.y = pk2(f0[2], f0[3]); v.z = pk2(f1[0], f1[1]); v.w = pk2(f1[2], f1[3]); }
;             else v = *(const u32x4*)(XBR + (size_t)(MP + bb * 8 + rr - 3) * DM + chA + c16 * 8);
;             *(LAS u32x4*)(xs + row * XS_PITCH + c16 * 16) = v; } }
.LBB0_860:
	s_or_b64 exec, exec, s[4:5]
	v_readfirstlane_b32 s4, v120
	s_mov_b64 s[54:55], 0x200
	s_nop 2
	s_ashr_i32 s4, s4, 6
	s_cmp_gt_i32 s4, 3
	s_barrier
	s_cbranch_scc1 .LBB0_892
	s_lshl_b32 s5, s66, 2
	v_readfirstlane_b32 s4, v120
	s_ashr_i32 s4, s4, 6
	s_add_i32 s5, s4, s5
	s_and_b32 s11, s5, 0xffffffe0
	s_lshl_b32 s6, s34, 7
	s_and_b32 s8, s4, 1
	v_and_b32_e32 v109, 31, v120
	s_add_i32 s11, s11, s6
	s_and_b32 s6, s5, 24
	s_lshl_b32 s5, s5, 5
	v_lshl_or_b32 v3, s8, 5, v109
	s_and_b32 s5, s5, 0x3c0
	v_lshlrev_b32_e32 v4, 11, v3
	v_mov_b32_e32 v5, v2
	v_or_b32_e32 v117, s5, v3
	v_lshl_add_u64 v[6:7], s[82:83], 0, v[4:5]
	s_lshl_b32 s34, s5, 1
	v_lshrrev_b32_e32 v3, 1, v120
	v_lshl_add_u64 v[4:5], s[84:85], 0, v[4:5]
	v_lshl_add_u64 v[6:7], v[6:7], 0, s[34:35]
	v_and_b32_e32 v8, 16, v3
	v_mov_b32_e32 v9, v2
	v_lshl_add_u64 v[4:5], v[4:5], 0, s[34:35]
	v_lshl_add_u64 v[10:11], v[6:7], 0, v[8:9]
	v_lshl_add_u64 v[8:9], v[4:5], 0, v[8:9]
	global_load_dwordx4 v[4:7], v[10:11], off
	global_load_dwordx4 v[20:23], v[8:9], off
	global_load_dwordx4 v[56:59], v[10:11], off offset:32
	global_load_dwordx4 v[52:55], v[8:9], off offset:32
	global_load_dwordx4 v[48:51], v[10:11], off offset:64
	global_load_dwordx4 v[44:47], v[8:9], off offset:64
	global_load_dwordx4 v[40:43], v[10:11], off offset:96
	global_load_dwordx4 v[36:39], v[8:9], off offset:96
	v_or_b32_e32 v8, s3, v117
	v_mov_b32_e32 v9, v2
	s_or_b32 s12, s11, s6
	s_mul_i32 s6, s4, 0x1900
	v_lshlrev_b64 v[8:9], 2, v[8:9]
	s_add_i32 s9, s6, 0
	s_mulk_i32 s4, 0xec00
	v_lshl_add_u64 v[10:11], s[80:81], 0, v[8:9]
	s_add_i32 s10, s9, s4
	global_load_dword v110, v[10:11], off
	v_lshl_add_u64 v[10:11], s[36:37], 0, v[8:9]
	s_lshl_b32 s4, s5, 2
	v_and_b32_e32 v116, 63, v120
	global_load_dword v3, v[10:11], off
	v_lshl_add_u64 v[10:11], s[38:39], 0, v[8:9]
	s_add_u32 s6, s86, s4
	global_load_dword v19, v[10:11], off
	v_lshlrev_b32_e32 v10, 2, v116
	v_lshlrev_b32_e32 v108, 2, v117
	s_addc_u32 s7, s87, 0
	global_load_dword v111, v108, s[86:87]
	global_load_dword v12, v10, s[6:7]
	global_load_dword v112, v108, s[92:93]
	s_add_u32 s6, s92, s4
	s_addc_u32 s7, s93, 0
	global_load_dword v13, v10, s[6:7]
	global_load_dword v113, v108, s[40:41]
	v_add_u32_e32 v11, s10, v10
	s_add_u32 s6, s40, s4
	s_addc_u32 s7, s41, 0
	v_lshl_add_u64 v[8:9], s[30:31], 0, v[8:9]
	v_and_b32_e32 v18, 7, v120
	v_bfe_u32 v118, v120, 3, 3
	v_cmp_lt_u32_e32 vcc, 23, v116
	s_waitcnt vmcnt(1)
	ds_write2st64_b32 v11, v12, v13 offset0:200 offset1:201
	global_load_dword v12, v10, s[6:7]
	global_load_dword v114, v108, s[42:43]
	global_load_dword v115, v[8:9], off
	v_or_b32_e32 v8, s3, v116
	v_or_b32_e32 v8, s5, v8
	v_mov_b32_e32 v9, v2
	s_add_u32 s6, s42, s4
	v_lshl_add_u64 v[8:9], v[8:9], 2, s[30:31]
	s_addc_u32 s7, s43, 0
	global_load_dword v8, v[8:9], off
	s_ashr_i32 s12, s12, 3
	global_load_dword v10, v10, s[6:7]
	s_and_b32 s14, s12, -4
	s_add_u32 s6, s27, s34
	s_addc_u32 s7, s76, 0
	v_mov_b32_e32 v9, v2
	s_waitcnt vmcnt(1)
	ds_write_b32 v11, v8 offset:52224
	v_lshlrev_b32_e32 v8, 4, v18
	s_waitcnt vmcnt(0)
	ds_write2st64_b32 v11, v12, v10 offset0:202 offset1:203
	v_lshl_add_u64 v[12:13], s[6:7], 0, v[8:9]
	s_and_saveexec_b64 s[6:7], vcc
	s_xor_b64 s[6:7], exec, s[6:7]
	s_cbranch_execz .LBB0_863
	v_lshl_or_b32 v8, s14, 3, v118
	v_add_u32_e32 v8, 0x3ffd, v8
	v_ashrrev_i32_e32 v9, 31, v8
	v_lshlrev_b64 v[8:9], 11, v[8:9]
	v_lshl_add_u64 v[8:9], v[12:13], 0, v[8:9]
	global_load_dwordx4 v[8:11], v[8:9], off
